# DA attention: waves 4-7 sleep 256 cycles after each KV-tile barrier (stagger the two waves of a SIMD)
# speedup vs baseline: 1.0103x; 1.0103x over previous
; #define PP (kp_get())
; __global__ void __launch_bounds__(512, 2) fwd_megakernel(Params P) {
;     ...
;         { const float lam = LAMS[l]; const float post = 1.f - (0.8f - 0.6f * expf(-0.3f * (float)l));
;           for (int r = 0;; ++r) { const int pos = (r & 1) ? G - 1 - c : c; const int idx = r * G + pos; if (idx >= 512) break;
;             const int qb = 15 - idx / 32, bh = idx % 32, b = bh >> 2, hh = bh & 3; const size_t off = (size_t)b * SEQ * 512 + hh * 128;
;             attn2_unit<true>(qb, (const bf16_t*)(PP->ws + WS_DQ) + off, (bf16_t*)(PP->ws + WS_DQ) + off, (const bf16_t*)(PP->ws + WS_DK) + off, (const bf16_t*)(PP->ws + WS_DV) + off, 4 * qb + 4, lam, PP->diff_subln + l * 128, post, lds); } }
.LBB0_669:
	v_readfirstlane_b32 s100, v196
	s_lshr_b32 s100, s100, 8
	v_readlane_b32 s12, v252, 28
	v_readlane_b32 s13, v252, 29
	s_mov_b64 s[30:31], s[0:1]
	s_and_b64 vcc, exec, s[12:13]
	s_cbranch_vccnz .LBB0_746
	s_load_dwordx2 s[12:13], s[30:31], 0xe0
	s_lshl_b64 s[14:15], s[48:49], 2
	v_mov_b32_e32 v0, 0x310000
	s_mov_b32 s25, 0
	s_mov_b32 s51, 0xda00000
	s_waitcnt lgkmcnt(0)
	s_add_u32 s12, s12, s14
	s_addc_u32 s13, s13, s15
	global_load_dword v198, v0, s[12:13]
	v_cvt_f32_u32_e32 v0, s48
	s_mov_b32 s12, 0x3fb8aa3b
	s_lshl_b32 s28, s48, 7
	s_lshl_b64 s[52:53], s[28:29], 2
	v_mul_f32_e32 v0, 0xbe99999a, v0
	v_mul_f32_e32 v2, 0x3fb8aa3b, v0
	v_fma_f32 v3, v0, s12, -v2
	v_rndne_f32_e32 v4, v2
	v_fmac_f32_e32 v3, 0x32a5705f, v0
	v_sub_f32_e32 v2, v2, v4
	v_add_f32_e32 v2, v2, v3
	v_exp_f32_e32 v2, v2
	v_cvt_i32_f32_e32 v3, v4
	s_mov_b32 s12, 0xc2ce8ed0
	v_cmp_ngt_f32_e32 vcc, s12, v0
	s_mov_b32 s12, 0x42b17218
	v_ldexp_f32 v2, v2, v3
	v_cndmask_b32_e32 v2, 0, v2, vcc
	v_mov_b32_e32 v3, 0x7f800000
	v_cmp_nlt_f32_e32 vcc, s12, v0
	s_mov_b32 s12, s2
	s_mov_b64 s[70:71], 0xda00000
	v_cndmask_b32_e32 v0, v3, v2, vcc
	v_mov_b32_e32 v2, 0xbf4ccccd
	v_fmamk_f32 v0, v0, 0x3f19999a, v2
	v_add_f32_e32 v199, 1.0, v0
	s_branch .LBB0_672

; template <bool DIFF>
; DI void attn2_unit(int qb, const bf16_t* QO  , bf16_t* Ob, const bf16_t* K, const bf16_t* V  ,
;                    int ntile, float lam, const float* gain, float post, LAS unsigned char* lds) {
;     ...
;         __syncthreads(); cur ^= 1;
;     }
.LBB0_674:
	s_cmp_eq_u32 s100, 0
	s_cbranch_scc1 .Lda_stg_skip
	s_sleep 4

; __global__ void __launch_bounds__(512, 2) fwd_megakernel(Params P) {
	.amdhsa_kernel _Z14fwd_megakernel6Params
		.amdhsa_group_segment_fixed_size 0
		.amdhsa_private_segment_fixed_size 0
		.amdhsa_kernarg_size 488
		.amdhsa_user_sgpr_count 2
		.amdhsa_user_sgpr_dispatch_ptr 0
		.amdhsa_user_sgpr_queue_ptr 0
		.amdhsa_user_sgpr_kernarg_segment_ptr 1
		.amdhsa_user_sgpr_dispatch_id 0
		.amdhsa_user_sgpr_kernarg_preload_length 0
		.amdhsa_user_sgpr_kernarg_preload_offset 0
		.amdhsa_user_sgpr_private_segment_size 0
		.amdhsa_uses_dynamic_stack 0
		.amdhsa_enable_private_segment 0
		.amdhsa_system_sgpr_workgroup_id_x 1
		.amdhsa_system_sgpr_workgroup_id_y 0
		.amdhsa_system_sgpr_workgroup_id_z 0
		.amdhsa_system_sgpr_workgroup_info 0
		.amdhsa_system_vgpr_workitem_id 2
		.amdhsa_next_free_vgpr 256
		.amdhsa_next_free_sgpr 102
		.amdhsa_accum_offset 256
		.amdhsa_reserve_vcc 1
		.amdhsa_float_round_mode_32 0
		.amdhsa_float_round_mode_16_64 0
		.amdhsa_float_denorm_mode_32 3
		.amdhsa_float_denorm_mode_16_64 3
		.amdhsa_dx10_clamp 1
		.amdhsa_ieee_mode 1
		.amdhsa_fp16_overflow 0
		.amdhsa_tg_split 0
		.amdhsa_exception_fp_ieee_invalid_op 0
		.amdhsa_exception_fp_denorm_src 0
		.amdhsa_exception_fp_ieee_div_zero 0
		.amdhsa_exception_fp_ieee_overflow 0
		.amdhsa_exception_fp_ieee_underflow 0
		.amdhsa_exception_fp_ieee_inexact 0
		.amdhsa_exception_int_div_zero 0
	.end_amdhsa_kernel

; __global__ void __launch_bounds__(512, 2) fwd_megakernel(Params P) {
amdhsa.kernels:
  - .agpr_count:     0
    .args:
      - .offset:         0
        .size:           232
        .value_kind:     by_value
      - .offset:         232
        .size:           4
        .value_kind:     hidden_block_count_x
      - .offset:         236
        .size:           4
        .value_kind:     hidden_block_count_y
      - .offset:         240
        .size:           4
        .value_kind:     hidden_block_count_z
      - .offset:         244
        .size:           2
        .value_kind:     hidden_group_size_x
      - .offset:         246
        .size:           2
        .value_kind:     hidden_group_size_y
      - .offset:         248
        .size:           2
        .value_kind:     hidden_group_size_z
      - .offset:         250
        .size:           2
        .value_kind:     hidden_remainder_x
      - .offset:         252
        .size:           2
        .value_kind:     hidden_remainder_y
      - .offset:         254
        .size:           2
        .value_kind:     hidden_remainder_z
      - .offset:         272
        .size:           8
        .value_kind:     hidden_global_offset_x
      - .offset:         280
        .size:           8
        .value_kind:     hidden_global_offset_y
      - .offset:         288
        .size:           8
        .value_kind:     hidden_global_offset_z
      - .offset:         296
        .size:           2
        .value_kind:     hidden_grid_dims
      - .offset:         320
        .size:           8
        .value_kind:     hidden_multigrid_sync_arg
      - .offset:         352
        .size:           4
        .value_kind:     hidden_dynamic_lds_size
    .group_segment_fixed_size: 0
    .kernarg_segment_align: 8
    .kernarg_segment_size: 488
    .language:       OpenCL C
    .language_version:
      - 2
      - 0
    .max_flat_workgroup_size: 512
    .name:           _Z14fwd_megakernel6Params
    .private_segment_fixed_size: 0
    .sgpr_count:     108
    .sgpr_spill_count: 305
    .symbol:         _Z14fwd_megakernel6Params.kd
    .uniform_work_group_size: 1
    .uses_dynamic_stack: false
    .vgpr_count:     256
    .vgpr_spill_count: 0
    .wavefront_size: 64
